# previous + final G4 epilogue: residual x1 loads batched 4x8 instead of 8 serialized round trips
# baseline (speedup 1.0000x reference)
; __device__ __forceinline__ void st_wt4(void* ptr, unsigned v) { asm volatile("global_store_dword %0, %1, off sc1" :: "v"(ptr), "v"(v) : "memory"); }
;     __device__ __forceinline__ void operator()(f32x4 (&acc)[2][2][4][2], const pg8::Unit& u, int wr, int wc, int fr, int fq) const {
;     ...
;             for (int m = 0; m < 4; ++m) {
;                 const int row = row0 + ai * 128 + m * 16;
;                 const float* xr = oy + (size_t)row * DM + col0;
;                 float q = 0.f;
; #pragma unroll
;                 for (int bj = 0; bj < 2; ++bj)
; #pragma unroll
;                     for (int n = 0; n < 2; ++n) {
;                         const f32x4 o = *(const f32x4*)(xr + bj * 128 + n * 16) + acc[ai][bj][m][n];
;                         acc[ai][bj][m][n] = o;
;                         q += (o[0] * o[0] + o[1] * o[1]) + (o[2] * o[2] + o[3] * o[3]);
;                     }
;                 q += __shfl_xor(q, 16); q += __shfl_xor(q, 32);
;                 if (fq == 0) st_wt4(ss + (size_t)row * 32 + u.pn * 4 + wc, __float_as_uint(q));
.LBB0_875:
	v_lshl_add_u32 v132, s44, 8, v180
	v_ashrrev_i32_e32 v133, 31, v132
	v_lshl_or_b32 v128, s10, 8, v182
	v_lshlrev_b64 v[130:131], 13, v[132:133]
	v_ashrrev_i32_e32 v129, 31, v128
	v_lshl_add_u64 v[130:131], s[84:85], 0, v[130:131]
	v_lshl_add_u64 v[150:151], v[128:129], 2, v[130:131]
	v_mov_b32_e32 v254, v150
	v_mov_b32_e32 v255, v151
	global_load_dwordx4 v[216:219], v[254:255], off
	global_load_dwordx4 v[220:223], v[254:255], off offset:64
	global_load_dwordx4 v[224:227], v[254:255], off offset:512
	global_load_dwordx4 v[228:231], v[254:255], off offset:576
	s_mov_b64 s[98:99], 0x20000
	v_lshl_add_u64 v[252:253], v[254:255], 0, s[98:99]
	global_load_dwordx4 v[236:239], v[252:253], off
	global_load_dwordx4 v[240:243], v[252:253], off offset:64
	global_load_dwordx4 v[244:247], v[252:253], off offset:512
	global_load_dwordx4 v[248:251], v[252:253], off offset:576
	s_waitcnt vmcnt(0)
	v_mov_b32_e32 v134, v216
	v_mov_b32_e32 v135, v217
	v_mov_b32_e32 v136, v218
	v_mov_b32_e32 v137, v219
	v_mov_b32_e32 v138, v220
	v_mov_b32_e32 v139, v221
	v_mov_b32_e32 v140, v222
	v_mov_b32_e32 v141, v223
	v_mov_b32_e32 v152, v224
	v_mov_b32_e32 v153, v225
	v_mov_b32_e32 v154, v226
	v_mov_b32_e32 v155, v227
	v_mov_b32_e32 v156, v228
	v_mov_b32_e32 v157, v229
	v_mov_b32_e32 v158, v230
	v_mov_b32_e32 v159, v231
	v_and_b32_e32 v131, 64, v195
	v_xor_b32_e32 v130, 16, v195
	v_add_u32_e32 v131, 64, v131
	v_cmp_lt_i32_e32 vcc, v130, v131
	s_lshl_b32 s36, s10, 2
	s_ashr_i32 s37, s36, 31
	v_cndmask_b32_e32 v130, v195, v130, vcc
	v_lshlrev_b32_e32 v185, 2, v130
	v_pk_add_f32 v[126:127], v[126:127], v[136:137]
	v_pk_add_f32 v[124:125], v[124:125], v[134:135]
	v_pk_add_f32 v[122:123], v[122:123], v[140:141]
	v_pk_add_f32 v[120:121], v[120:121], v[138:139]
	v_pk_add_f32 v[94:95], v[94:95], v[154:155]
	v_pk_add_f32 v[92:93], v[92:93], v[152:153]
	v_mul_f32_e32 v130, v125, v125
	v_mul_f32_e32 v134, v127, v127
	v_mul_f32_e32 v135, v121, v121
	v_mul_f32_e32 v136, v123, v123
	v_pk_add_f32 v[90:91], v[90:91], v[158:159]
	v_pk_add_f32 v[88:89], v[88:89], v[156:157]
	v_mul_f32_e32 v137, v93, v93
	v_mul_f32_e32 v138, v95, v95
	v_fmac_f32_e32 v130, v124, v124
	v_fmac_f32_e32 v134, v126, v126
	v_fmac_f32_e32 v135, v120, v120
	v_fmac_f32_e32 v136, v122, v122
	v_mul_f32_e32 v139, v89, v89
	v_mul_f32_e32 v140, v91, v91
	v_fmac_f32_e32 v137, v92, v92
	v_fmac_f32_e32 v138, v94, v94
	v_add_f32_e32 v130, v130, v134
	v_add_f32_e32 v134, v135, v136
	v_fmac_f32_e32 v139, v88, v88
	v_fmac_f32_e32 v140, v90, v90
	v_add_f32_e32 v135, v137, v138
	v_add_f32_e32 v130, v130, v134
	v_add_f32_e32 v130, v130, v135
	v_add_f32_e32 v134, v139, v140
	v_add_f32_e32 v130, v130, v134
	ds_bpermute_b32 v134, v185, v130
	v_xor_b32_e32 v135, 32, v195
	v_cmp_lt_i32_e32 vcc, v135, v131
	s_waitcnt lgkmcnt(0)
	v_add_f32_e32 v134, v130, v134
	v_cndmask_b32_e32 v131, v195, v135, vcc
	v_lshlrev_b32_e32 v186, 2, v131
	ds_bpermute_b32 v135, v186, v134
	v_lshlrev_b64 v[130:131], 7, v[132:133]
	s_and_saveexec_b64 s[38:39], s[4:5]
	s_cbranch_execz .LBB0_877
	s_waitcnt lgkmcnt(0)
	v_add_f32_e32 v133, v134, v135
	v_lshl_add_u64 v[134:135], s[0:1], 0, v[130:131]
	v_lshl_add_u64 v[134:135], s[36:37], 2, v[134:135]
	s_lshl_b32 s16, s53, 2
	v_lshl_add_u64 v[134:135], v[134:135], 0, s[16:17]
	global_store_dword v[134:135], v133, off sc1
.LBB0_877:
	s_or_b64 exec, exec, s[38:39]
	v_or_b32_e32 v142, 16, v132
	v_ashrrev_i32_e32 v143, 31, v142
	s_waitcnt lgkmcnt(0)
	v_lshlrev_b64 v[134:135], 13, v[142:143]
	v_lshl_add_u64 v[134:135], s[84:85], 0, v[134:135]
	v_lshl_add_u64 v[152:153], v[128:129], 2, v[134:135]
	v_mov_b32_e32 v134, v236
	v_mov_b32_e32 v135, v237
	v_mov_b32_e32 v136, v238
	v_mov_b32_e32 v137, v239
	v_mov_b32_e32 v138, v240
	v_mov_b32_e32 v139, v241
	v_mov_b32_e32 v140, v242
	v_mov_b32_e32 v141, v243
	v_mov_b32_e32 v154, v244
	v_mov_b32_e32 v155, v245
	v_mov_b32_e32 v156, v246
	v_mov_b32_e32 v157, v247
	v_mov_b32_e32 v158, v248
	v_mov_b32_e32 v159, v249
	v_mov_b32_e32 v160, v250
	v_mov_b32_e32 v161, v251
	v_lshlrev_b64 v[166:167], 7, v[142:143]
	v_pk_add_f32 v[118:119], v[118:119], v[136:137]
	v_pk_add_f32 v[116:117], v[116:117], v[134:135]
	v_pk_add_f32 v[114:115], v[114:115], v[140:141]
	v_pk_add_f32 v[112:113], v[112:113], v[138:139]
	v_pk_add_f32 v[86:87], v[86:87], v[156:157]
	v_pk_add_f32 v[84:85], v[84:85], v[154:155]
	v_mul_f32_e32 v133, v117, v117
	v_mul_f32_e32 v134, v119, v119
	v_mul_f32_e32 v135, v113, v113
	v_mul_f32_e32 v136, v115, v115
	v_pk_add_f32 v[82:83], v[82:83], v[160:161]
	v_pk_add_f32 v[80:81], v[80:81], v[158:159]
	v_mul_f32_e32 v137, v85, v85
	v_mul_f32_e32 v138, v87, v87
	v_fmac_f32_e32 v133, v116, v116
	v_fmac_f32_e32 v134, v118, v118
	v_fmac_f32_e32 v135, v112, v112
	v_fmac_f32_e32 v136, v114, v114
	v_mul_f32_e32 v139, v81, v81
	v_mul_f32_e32 v140, v83, v83
	v_fmac_f32_e32 v137, v84, v84
	v_fmac_f32_e32 v138, v86, v86
	v_add_f32_e32 v133, v133, v134
	v_add_f32_e32 v134, v135, v136
	v_fmac_f32_e32 v139, v80, v80
	v_fmac_f32_e32 v140, v82, v82
	v_add_f32_e32 v135, v137, v138
	v_add_f32_e32 v133, v133, v134
	v_add_f32_e32 v133, v133, v135
	v_add_f32_e32 v134, v139, v140
	v_add_f32_e32 v133, v133, v134
	ds_bpermute_b32 v134, v185, v133
	s_waitcnt lgkmcnt(0)
	v_add_f32_e32 v133, v133, v134
	ds_bpermute_b32 v134, v186, v133
	s_and_saveexec_b64 s[38:39], s[4:5]
	s_cbranch_execz .LBB0_879
	s_waitcnt lgkmcnt(0)
	v_add_f32_e32 v133, v133, v134
	v_lshl_add_u64 v[134:135], s[0:1], 0, v[166:167]
	v_lshl_add_u64 v[134:135], s[36:37], 2, v[134:135]
	s_lshl_b32 s16, s53, 2
	v_lshl_add_u64 v[134:135], v[134:135], 0, s[16:17]
	global_store_dword v[134:135], v133, off sc1
; __device__ __forceinline__ void st_wt4(void* ptr, unsigned v) { asm volatile("global_store_dword %0, %1, off sc1" :: "v"(ptr), "v"(v) : "memory"); }
;     __device__ __forceinline__ void operator()(f32x4 (&acc)[2][2][4][2], const pg8::Unit& u, int wr, int wc, int fr, int fq) const {
;     ...
;             for (int m = 0; m < 4; ++m) {
;                 const int row = row0 + ai * 128 + m * 16;
;                 const float* xr = oy + (size_t)row * DM + col0;
;                 float q = 0.f;
; #pragma unroll
;                 for (int bj = 0; bj < 2; ++bj)
; #pragma unroll
;                     for (int n = 0; n < 2; ++n) {
;                         const f32x4 o = *(const f32x4*)(xr + bj * 128 + n * 16) + acc[ai][bj][m][n];
;                         acc[ai][bj][m][n] = o;
;                         q += (o[0] * o[0] + o[1] * o[1]) + (o[2] * o[2] + o[3] * o[3]);
;                     }
;                 q += __shfl_xor(q, 16); q += __shfl_xor(q, 32);
;                 if (fq == 0) st_wt4(ss + (size_t)row * 32 + u.pn * 4 + wc, __float_as_uint(q));
.LBB0_879:
	s_or_b64 exec, exec, s[38:39]
	v_or_b32_e32 v142, 32, v132
	v_ashrrev_i32_e32 v143, 31, v142
	s_waitcnt lgkmcnt(0)
	v_lshlrev_b64 v[134:135], 13, v[142:143]
	v_lshl_add_u64 v[134:135], s[84:85], 0, v[134:135]
	v_lshl_add_u64 v[154:155], v[128:129], 2, v[134:135]
	s_mov_b64 s[98:99], 0x40000
	v_lshl_add_u64 v[252:253], v[254:255], 0, s[98:99]
	global_load_dwordx4 v[216:219], v[252:253], off
	global_load_dwordx4 v[220:223], v[252:253], off offset:64
	global_load_dwordx4 v[224:227], v[252:253], off offset:512
	global_load_dwordx4 v[228:231], v[252:253], off offset:576
	s_mov_b64 s[98:99], 0x60000
	v_lshl_add_u64 v[252:253], v[254:255], 0, s[98:99]
	global_load_dwordx4 v[236:239], v[252:253], off
	global_load_dwordx4 v[240:243], v[252:253], off offset:64
	global_load_dwordx4 v[244:247], v[252:253], off offset:512
	global_load_dwordx4 v[248:251], v[252:253], off offset:576
	s_waitcnt vmcnt(0)
	v_mov_b32_e32 v134, v216
	v_mov_b32_e32 v135, v217
	v_mov_b32_e32 v136, v218
	v_mov_b32_e32 v137, v219
	v_mov_b32_e32 v138, v220
	v_mov_b32_e32 v139, v221
	v_mov_b32_e32 v140, v222
	v_mov_b32_e32 v141, v223
	v_mov_b32_e32 v156, v224
	v_mov_b32_e32 v157, v225
	v_mov_b32_e32 v158, v226
	v_mov_b32_e32 v159, v227
	v_mov_b32_e32 v160, v228
	v_mov_b32_e32 v161, v229
	v_mov_b32_e32 v162, v230
	v_mov_b32_e32 v163, v231
	v_lshlrev_b64 v[168:169], 7, v[142:143]
	v_pk_add_f32 v[110:111], v[110:111], v[136:137]
	v_pk_add_f32 v[108:109], v[108:109], v[134:135]
	v_pk_add_f32 v[106:107], v[106:107], v[140:141]
	v_pk_add_f32 v[104:105], v[104:105], v[138:139]
	v_pk_add_f32 v[78:79], v[78:79], v[158:159]
	v_pk_add_f32 v[76:77], v[76:77], v[156:157]
	v_mul_f32_e32 v133, v109, v109
	v_mul_f32_e32 v134, v111, v111
	v_mul_f32_e32 v135, v105, v105
	v_mul_f32_e32 v136, v107, v107
	v_pk_add_f32 v[74:75], v[74:75], v[162:163]
	v_pk_add_f32 v[72:73], v[72:73], v[160:161]
	v_mul_f32_e32 v137, v77, v77
	v_mul_f32_e32 v138, v79, v79
	v_fmac_f32_e32 v133, v108, v108
	v_fmac_f32_e32 v134, v110, v110
	v_fmac_f32_e32 v135, v104, v104
	v_fmac_f32_e32 v136, v106, v106
	v_mul_f32_e32 v139, v73, v73
	v_mul_f32_e32 v140, v75, v75
	v_fmac_f32_e32 v137, v76, v76
	v_fmac_f32_e32 v138, v78, v78
	v_add_f32_e32 v133, v133, v134
	v_add_f32_e32 v134, v135, v136
	v_fmac_f32_e32 v139, v72, v72
	v_fmac_f32_e32 v140, v74, v74
	v_add_f32_e32 v135, v137, v138
	v_add_f32_e32 v133, v133, v134
	v_add_f32_e32 v133, v133, v135
	v_add_f32_e32 v134, v139, v140
	v_add_f32_e32 v133, v133, v134
	ds_bpermute_b32 v134, v185, v133
	s_waitcnt lgkmcnt(0)
	v_add_f32_e32 v133, v133, v134
	ds_bpermute_b32 v134, v186, v133
	s_and_saveexec_b64 s[38:39], s[4:5]
	s_cbranch_execz .LBB0_881
	s_waitcnt lgkmcnt(0)
	v_add_f32_e32 v133, v133, v134
	v_lshl_add_u64 v[134:135], s[0:1], 0, v[168:169]
	v_lshl_add_u64 v[134:135], s[36:37], 2, v[134:135]
	s_lshl_b32 s16, s53, 2
	v_lshl_add_u64 v[134:135], v[134:135], 0, s[16:17]
	global_store_dword v[134:135], v133, off sc1
.LBB0_881:
	s_or_b64 exec, exec, s[38:39]
	v_or_b32_e32 v142, 48, v132
	v_ashrrev_i32_e32 v143, 31, v142
	s_waitcnt lgkmcnt(0)
	v_lshlrev_b64 v[134:135], 13, v[142:143]
	v_lshl_add_u64 v[134:135], s[84:85], 0, v[134:135]
	v_lshl_add_u64 v[156:157], v[128:129], 2, v[134:135]
	v_mov_b32_e32 v134, v236
	v_mov_b32_e32 v135, v237
	v_mov_b32_e32 v136, v238
	v_mov_b32_e32 v137, v239
	v_mov_b32_e32 v138, v240
	v_mov_b32_e32 v139, v241
	v_mov_b32_e32 v140, v242
	v_mov_b32_e32 v141, v243
	v_mov_b32_e32 v158, v244
	v_mov_b32_e32 v159, v245
	v_mov_b32_e32 v160, v246
	v_mov_b32_e32 v161, v247
	v_mov_b32_e32 v162, v248
	v_mov_b32_e32 v163, v249
	v_mov_b32_e32 v164, v250
	v_mov_b32_e32 v165, v251
	v_lshlrev_b64 v[170:171], 7, v[142:143]
	v_pk_add_f32 v[102:103], v[102:103], v[136:137]
	v_pk_add_f32 v[100:101], v[100:101], v[134:135]
	v_pk_add_f32 v[98:99], v[98:99], v[140:141]
	v_pk_add_f32 v[96:97], v[96:97], v[138:139]
	v_pk_add_f32 v[70:71], v[70:71], v[160:161]
	v_pk_add_f32 v[68:69], v[68:69], v[158:159]
	v_mul_f32_e32 v133, v101, v101
	v_mul_f32_e32 v134, v103, v103
	v_mul_f32_e32 v135, v97, v97
	v_mul_f32_e32 v136, v99, v99
	v_pk_add_f32 v[66:67], v[66:67], v[164:165]
	v_pk_add_f32 v[64:65], v[64:65], v[162:163]
	v_mul_f32_e32 v137, v69, v69
	v_mul_f32_e32 v138, v71, v71
	v_fmac_f32_e32 v133, v100, v100
	v_fmac_f32_e32 v134, v102, v102
	v_fmac_f32_e32 v135, v96, v96
	v_fmac_f32_e32 v136, v98, v98
	v_mul_f32_e32 v139, v65, v65
	v_mul_f32_e32 v140, v67, v67
	v_fmac_f32_e32 v137, v68, v68
	v_fmac_f32_e32 v138, v70, v70
	v_add_f32_e32 v133, v133, v134
	v_add_f32_e32 v134, v135, v136
	v_fmac_f32_e32 v139, v64, v64
	v_fmac_f32_e32 v140, v66, v66
	v_add_f32_e32 v135, v137, v138
	v_add_f32_e32 v133, v133, v134
	v_add_f32_e32 v133, v133, v135
	v_add_f32_e32 v134, v139, v140
	v_add_f32_e32 v133, v133, v134
	ds_bpermute_b32 v134, v185, v133
	s_waitcnt lgkmcnt(0)
	v_add_f32_e32 v133, v133, v134
	ds_bpermute_b32 v134, v186, v133
	s_and_saveexec_b64 s[38:39], s[4:5]
	s_cbranch_execz .LBB0_883
	s_waitcnt lgkmcnt(0)
	v_add_f32_e32 v133, v133, v134
	v_lshl_add_u64 v[134:135], s[0:1], 0, v[170:171]
	v_lshl_add_u64 v[134:135], s[36:37], 2, v[134:135]
	s_lshl_b32 s16, s53, 2
	v_lshl_add_u64 v[134:135], v[134:135], 0, s[16:17]
	global_store_dword v[134:135], v133, off sc1
; __device__ __forceinline__ void st_wt4(void* ptr, unsigned v) { asm volatile("global_store_dword %0, %1, off sc1" :: "v"(ptr), "v"(v) : "memory"); }
;     __device__ __forceinline__ void operator()(f32x4 (&acc)[2][2][4][2], const pg8::Unit& u, int wr, int wc, int fr, int fq) const {
;     ...
;             for (int m = 0; m < 4; ++m) {
;                 const int row = row0 + ai * 128 + m * 16;
;                 const float* xr = oy + (size_t)row * DM + col0;
;                 float q = 0.f;
; #pragma unroll
;                 for (int bj = 0; bj < 2; ++bj)
; #pragma unroll
;                     for (int n = 0; n < 2; ++n) {
;                         const f32x4 o = *(const f32x4*)(xr + bj * 128 + n * 16) + acc[ai][bj][m][n];
;                         acc[ai][bj][m][n] = o;
;                         q += (o[0] * o[0] + o[1] * o[1]) + (o[2] * o[2] + o[3] * o[3]);
;                     }
;                 q += __shfl_xor(q, 16); q += __shfl_xor(q, 32);
;                 if (fq == 0) st_wt4(ss + (size_t)row * 32 + u.pn * 4 + wc, __float_as_uint(q));
.LBB0_883:
	s_or_b64 exec, exec, s[38:39]
	v_add_u32_e32 v142, 0x80, v132
	v_ashrrev_i32_e32 v143, 31, v142
	s_waitcnt lgkmcnt(0)
	v_lshlrev_b64 v[134:135], 13, v[142:143]
	v_lshl_add_u64 v[134:135], s[84:85], 0, v[134:135]
	v_lshl_add_u64 v[158:159], v[128:129], 2, v[134:135]
	s_mov_b64 s[98:99], 0x100000
	v_lshl_add_u64 v[252:253], v[254:255], 0, s[98:99]
	global_load_dwordx4 v[216:219], v[252:253], off
	global_load_dwordx4 v[220:223], v[252:253], off offset:64
	global_load_dwordx4 v[224:227], v[252:253], off offset:512
	global_load_dwordx4 v[228:231], v[252:253], off offset:576
	s_mov_b64 s[98:99], 0x120000
	v_lshl_add_u64 v[252:253], v[254:255], 0, s[98:99]
	global_load_dwordx4 v[236:239], v[252:253], off
	global_load_dwordx4 v[240:243], v[252:253], off offset:64
	global_load_dwordx4 v[244:247], v[252:253], off offset:512
	global_load_dwordx4 v[248:251], v[252:253], off offset:576
	s_waitcnt vmcnt(0)
	v_mov_b32_e32 v134, v216
	v_mov_b32_e32 v135, v217
	v_mov_b32_e32 v136, v218
	v_mov_b32_e32 v137, v219
	v_mov_b32_e32 v138, v220
	v_mov_b32_e32 v139, v221
	v_mov_b32_e32 v140, v222
	v_mov_b32_e32 v141, v223
	v_mov_b32_e32 v160, v224
	v_mov_b32_e32 v161, v225
	v_mov_b32_e32 v162, v226
	v_mov_b32_e32 v163, v227
	v_mov_b32_e32 v172, v228
	v_mov_b32_e32 v173, v229
	v_mov_b32_e32 v174, v230
	v_mov_b32_e32 v175, v231
	v_pk_add_f32 v[62:63], v[62:63], v[136:137]
	v_pk_add_f32 v[60:61], v[60:61], v[134:135]
	v_pk_add_f32 v[58:59], v[58:59], v[140:141]
	v_pk_add_f32 v[56:57], v[56:57], v[138:139]
	v_pk_add_f32 v[30:31], v[30:31], v[162:163]
	v_pk_add_f32 v[28:29], v[28:29], v[160:161]
	v_mul_f32_e32 v133, v61, v61
	v_mul_f32_e32 v134, v63, v63
	v_mul_f32_e32 v135, v57, v57
	v_mul_f32_e32 v136, v59, v59
	v_pk_add_f32 v[26:27], v[26:27], v[174:175]
	v_pk_add_f32 v[24:25], v[24:25], v[172:173]
	v_mul_f32_e32 v137, v29, v29
	v_mul_f32_e32 v138, v31, v31
	v_fmac_f32_e32 v133, v60, v60
	v_fmac_f32_e32 v134, v62, v62
	v_fmac_f32_e32 v135, v56, v56
	v_fmac_f32_e32 v136, v58, v58
	v_mul_f32_e32 v139, v25, v25
	v_mul_f32_e32 v140, v27, v27
	v_fmac_f32_e32 v137, v28, v28
	v_fmac_f32_e32 v138, v30, v30
	v_add_f32_e32 v133, v133, v134
	v_add_f32_e32 v134, v135, v136
	v_fmac_f32_e32 v139, v24, v24
	v_fmac_f32_e32 v140, v26, v26
	v_add_f32_e32 v135, v137, v138
	v_add_f32_e32 v133, v133, v134
	v_add_f32_e32 v133, v133, v135
	v_add_f32_e32 v134, v139, v140
	v_add_f32_e32 v133, v133, v134
	ds_bpermute_b32 v134, v185, v133
	v_lshlrev_b64 v[172:173], 7, v[142:143]
	s_waitcnt lgkmcnt(0)
	v_add_f32_e32 v133, v133, v134
	ds_bpermute_b32 v134, v186, v133
	s_and_saveexec_b64 s[38:39], s[4:5]
	s_cbranch_execz .LBB0_885
	s_waitcnt lgkmcnt(0)
	v_add_f32_e32 v133, v133, v134
	v_lshl_add_u64 v[134:135], s[0:1], 0, v[172:173]
	v_lshl_add_u64 v[134:135], s[36:37], 2, v[134:135]
	s_lshl_b32 s16, s53, 2
	v_lshl_add_u64 v[134:135], v[134:135], 0, s[16:17]
	global_store_dword v[134:135], v133, off sc1
.LBB0_885:
	s_or_b64 exec, exec, s[38:39]
	v_add_u32_e32 v142, 0x90, v132
	v_ashrrev_i32_e32 v143, 31, v142
	s_waitcnt lgkmcnt(0)
	v_lshlrev_b64 v[134:135], 13, v[142:143]
	v_lshl_add_u64 v[134:135], s[84:85], 0, v[134:135]
	v_lshl_add_u64 v[160:161], v[128:129], 2, v[134:135]
	v_mov_b32_e32 v134, v236
	v_mov_b32_e32 v135, v237
	v_mov_b32_e32 v136, v238
	v_mov_b32_e32 v137, v239
	v_mov_b32_e32 v138, v240
	v_mov_b32_e32 v139, v241
	v_mov_b32_e32 v140, v242
	v_mov_b32_e32 v141, v243
	v_mov_b32_e32 v162, v244
	v_mov_b32_e32 v163, v245
	v_mov_b32_e32 v164, v246
	v_mov_b32_e32 v165, v247
	v_mov_b32_e32 v174, v248
	v_mov_b32_e32 v175, v249
	v_mov_b32_e32 v176, v250
	v_mov_b32_e32 v177, v251
	v_pk_add_f32 v[54:55], v[54:55], v[136:137]
	v_pk_add_f32 v[52:53], v[52:53], v[134:135]
	v_pk_add_f32 v[50:51], v[50:51], v[140:141]
	v_pk_add_f32 v[48:49], v[48:49], v[138:139]
	v_pk_add_f32 v[22:23], v[22:23], v[164:165]
	v_pk_add_f32 v[20:21], v[20:21], v[162:163]
	v_mul_f32_e32 v133, v53, v53
	v_mul_f32_e32 v134, v55, v55
	v_mul_f32_e32 v135, v49, v49
	v_mul_f32_e32 v136, v51, v51
	v_pk_add_f32 v[18:19], v[18:19], v[176:177]
	v_pk_add_f32 v[16:17], v[16:17], v[174:175]
	v_mul_f32_e32 v137, v21, v21
	v_mul_f32_e32 v138, v23, v23
	v_fmac_f32_e32 v133, v52, v52
	v_fmac_f32_e32 v134, v54, v54
	v_fmac_f32_e32 v135, v48, v48
	v_fmac_f32_e32 v136, v50, v50
	v_mul_f32_e32 v139, v17, v17
	v_mul_f32_e32 v140, v19, v19
	v_fmac_f32_e32 v137, v20, v20
	v_fmac_f32_e32 v138, v22, v22
	v_add_f32_e32 v133, v133, v134
	v_add_f32_e32 v134, v135, v136
	v_fmac_f32_e32 v139, v16, v16
	v_fmac_f32_e32 v140, v18, v18
	v_add_f32_e32 v135, v137, v138
	v_add_f32_e32 v133, v133, v134
	v_add_f32_e32 v133, v133, v135
	v_add_f32_e32 v134, v139, v140
	v_add_f32_e32 v133, v133, v134
	ds_bpermute_b32 v134, v185, v133
	v_lshlrev_b64 v[174:175], 7, v[142:143]
	s_waitcnt lgkmcnt(0)
	v_add_f32_e32 v133, v133, v134
	ds_bpermute_b32 v134, v186, v133
	s_and_saveexec_b64 s[38:39], s[4:5]
	s_cbranch_execz .LBB0_887
	s_waitcnt lgkmcnt(0)
	v_add_f32_e32 v133, v133, v134
	v_lshl_add_u64 v[134:135], s[0:1], 0, v[174:175]
	v_lshl_add_u64 v[134:135], s[36:37], 2, v[134:135]
	s_lshl_b32 s16, s53, 2
	v_lshl_add_u64 v[134:135], v[134:135], 0, s[16:17]
	global_store_dword v[134:135], v133, off sc1
; __device__ __forceinline__ void st_wt4(void* ptr, unsigned v) { asm volatile("global_store_dword %0, %1, off sc1" :: "v"(ptr), "v"(v) : "memory"); }
;     __device__ __forceinline__ void operator()(f32x4 (&acc)[2][2][4][2], const pg8::Unit& u, int wr, int wc, int fr, int fq) const {
;     ...
;             for (int m = 0; m < 4; ++m) {
;                 const int row = row0 + ai * 128 + m * 16;
;                 const float* xr = oy + (size_t)row * DM + col0;
;                 float q = 0.f;
; #pragma unroll
;                 for (int bj = 0; bj < 2; ++bj)
; #pragma unroll
;                     for (int n = 0; n < 2; ++n) {
;                         const f32x4 o = *(const f32x4*)(xr + bj * 128 + n * 16) + acc[ai][bj][m][n];
;                         acc[ai][bj][m][n] = o;
;                         q += (o[0] * o[0] + o[1] * o[1]) + (o[2] * o[2] + o[3] * o[3]);
;                     }
;                 q += __shfl_xor(q, 16); q += __shfl_xor(q, 32);
;                 if (fq == 0) st_wt4(ss + (size_t)row * 32 + u.pn * 4 + wc, __float_as_uint(q));
.LBB0_887:
	s_or_b64 exec, exec, s[38:39]
	v_add_u32_e32 v142, 0xa0, v132
	v_ashrrev_i32_e32 v143, 31, v142
	s_waitcnt lgkmcnt(0)
	v_lshlrev_b64 v[134:135], 13, v[142:143]
	v_lshl_add_u64 v[134:135], s[84:85], 0, v[134:135]
	v_lshl_add_u64 v[162:163], v[128:129], 2, v[134:135]
	s_mov_b64 s[98:99], 0x140000
	v_lshl_add_u64 v[252:253], v[254:255], 0, s[98:99]
	global_load_dwordx4 v[216:219], v[252:253], off
	global_load_dwordx4 v[220:223], v[252:253], off offset:64
	global_load_dwordx4 v[224:227], v[252:253], off offset:512
	global_load_dwordx4 v[228:231], v[252:253], off offset:576
	s_mov_b64 s[98:99], 0x160000
	v_lshl_add_u64 v[252:253], v[254:255], 0, s[98:99]
	global_load_dwordx4 v[236:239], v[252:253], off
	global_load_dwordx4 v[240:243], v[252:253], off offset:64
	global_load_dwordx4 v[244:247], v[252:253], off offset:512
	global_load_dwordx4 v[248:251], v[252:253], off offset:576
	s_waitcnt vmcnt(0)
	v_mov_b32_e32 v134, v216
	v_mov_b32_e32 v135, v217
	v_mov_b32_e32 v136, v218
	v_mov_b32_e32 v137, v219
	v_mov_b32_e32 v138, v220
	v_mov_b32_e32 v139, v221
	v_mov_b32_e32 v140, v222
	v_mov_b32_e32 v141, v223
	v_mov_b32_e32 v176, v224
	v_mov_b32_e32 v177, v225
	v_mov_b32_e32 v178, v226
	v_mov_b32_e32 v179, v227
	v_mov_b32_e32 v188, v228
	v_mov_b32_e32 v189, v229
	v_mov_b32_e32 v190, v230
	v_mov_b32_e32 v191, v231
	v_pk_add_f32 v[46:47], v[46:47], v[136:137]
	v_pk_add_f32 v[44:45], v[44:45], v[134:135]
	v_pk_add_f32 v[42:43], v[42:43], v[140:141]
	v_pk_add_f32 v[40:41], v[40:41], v[138:139]
	v_pk_add_f32 v[14:15], v[14:15], v[178:179]
	v_pk_add_f32 v[12:13], v[12:13], v[176:177]
	v_mul_f32_e32 v133, v45, v45
	v_mul_f32_e32 v134, v47, v47
	v_mul_f32_e32 v135, v41, v41
	v_mul_f32_e32 v136, v43, v43
	v_pk_add_f32 v[10:11], v[10:11], v[190:191]
	v_pk_add_f32 v[8:9], v[8:9], v[188:189]
	v_mul_f32_e32 v137, v13, v13
	v_mul_f32_e32 v138, v15, v15
	v_fmac_f32_e32 v133, v44, v44
	v_fmac_f32_e32 v134, v46, v46
	v_fmac_f32_e32 v135, v40, v40
	v_fmac_f32_e32 v136, v42, v42
	v_mul_f32_e32 v139, v9, v9
	v_mul_f32_e32 v140, v11, v11
	v_fmac_f32_e32 v137, v12, v12
	v_fmac_f32_e32 v138, v14, v14
	v_add_f32_e32 v133, v133, v134
	v_add_f32_e32 v134, v135, v136
	v_fmac_f32_e32 v139, v8, v8
	v_fmac_f32_e32 v140, v10, v10
	v_add_f32_e32 v135, v137, v138
	v_add_f32_e32 v133, v133, v134
	v_add_f32_e32 v133, v133, v135
	v_add_f32_e32 v134, v139, v140
	v_add_f32_e32 v133, v133, v134
	ds_bpermute_b32 v134, v185, v133
	v_lshlrev_b64 v[176:177], 7, v[142:143]
	s_waitcnt lgkmcnt(0)
	v_add_f32_e32 v133, v133, v134
	ds_bpermute_b32 v134, v186, v133
	s_and_saveexec_b64 s[38:39], s[4:5]
	s_cbranch_execz .LBB0_889
	s_waitcnt lgkmcnt(0)
	v_add_f32_e32 v133, v133, v134
	v_lshl_add_u64 v[134:135], s[0:1], 0, v[176:177]
	v_lshl_add_u64 v[134:135], s[36:37], 2, v[134:135]
	s_lshl_b32 s16, s53, 2
	v_lshl_add_u64 v[134:135], v[134:135], 0, s[16:17]
	global_store_dword v[134:135], v133, off sc1
.LBB0_889:
	s_or_b64 exec, exec, s[38:39]
	v_add_u32_e32 v178, 0xb0, v132
	v_ashrrev_i32_e32 v179, 31, v178
	v_lshlrev_b64 v[132:133], 13, v[178:179]
	v_lshl_add_u64 v[132:133], s[84:85], 0, v[132:133]
	v_lshl_add_u64 v[164:165], v[128:129], 2, v[132:133]
	s_waitcnt lgkmcnt(0)
	v_mov_b32_e32 v132, v236
	v_mov_b32_e32 v133, v237
	v_mov_b32_e32 v134, v238
	v_mov_b32_e32 v135, v239
	v_mov_b32_e32 v136, v240
	v_mov_b32_e32 v137, v241
	v_mov_b32_e32 v138, v242
	v_mov_b32_e32 v139, v243
	v_mov_b32_e32 v140, v244
	v_mov_b32_e32 v141, v245
	v_mov_b32_e32 v142, v246
	v_mov_b32_e32 v143, v247
	v_mov_b32_e32 v188, v248
	v_mov_b32_e32 v189, v249
	v_mov_b32_e32 v190, v250
	v_mov_b32_e32 v191, v251
	v_lshlrev_b64 v[178:179], 7, v[178:179]
	v_pk_add_f32 v[38:39], v[38:39], v[134:135]
	v_pk_add_f32 v[36:37], v[36:37], v[132:133]
	v_pk_add_f32 v[34:35], v[34:35], v[138:139]
	v_pk_add_f32 v[32:33], v[32:33], v[136:137]
	v_pk_add_f32 v[6:7], v[6:7], v[142:143]
	v_pk_add_f32 v[4:5], v[4:5], v[140:141]
	v_mul_f32_e32 v132, v37, v37
	v_mul_f32_e32 v133, v39, v39
	v_mul_f32_e32 v134, v33, v33
	v_mul_f32_e32 v135, v35, v35
	v_pk_add_f32 v[2:3], v[2:3], v[190:191]
	v_pk_add_f32 v[0:1], v[0:1], v[188:189]
	v_mul_f32_e32 v136, v5, v5
	v_mul_f32_e32 v137, v7, v7
	v_fmac_f32_e32 v132, v36, v36
	v_fmac_f32_e32 v133, v38, v38
	v_fmac_f32_e32 v134, v32, v32
	v_fmac_f32_e32 v135, v34, v34
	v_mul_f32_e32 v138, v1, v1
	v_mul_f32_e32 v139, v3, v3
	v_fmac_f32_e32 v136, v4, v4
	v_fmac_f32_e32 v137, v6, v6
	v_add_f32_e32 v132, v132, v133
	v_add_f32_e32 v133, v134, v135
	v_fmac_f32_e32 v138, v0, v0
	v_fmac_f32_e32 v139, v2, v2
	v_add_f32_e32 v134, v136, v137
	v_add_f32_e32 v132, v132, v133
	v_add_f32_e32 v132, v132, v134
	v_add_f32_e32 v133, v138, v139
	v_add_f32_e32 v132, v132, v133
	ds_bpermute_b32 v133, v185, v132
	s_waitcnt lgkmcnt(0)
	v_add_f32_e32 v132, v132, v133
	ds_bpermute_b32 v133, v186, v132
	s_and_saveexec_b64 s[38:39], s[4:5]
	s_cbranch_execz .LBB0_891
	s_waitcnt lgkmcnt(0)
	v_add_f32_e32 v134, v132, v133
	v_lshl_add_u64 v[132:133], s[0:1], 0, v[178:179]
	v_lshl_add_u64 v[132:133], s[36:37], 2, v[132:133]
	s_lshl_b32 s16, s53, 2
	v_lshl_add_u64 v[132:133], v[132:133], 0, s[16:17]
	global_store_dword v[132:133], v134, off sc1

; __global__ void __launch_bounds__(512, 2) fwd_megakernel(Params p) {
	.amdhsa_kernel _Z14fwd_megakernel6Params
		.amdhsa_group_segment_fixed_size 0
		.amdhsa_private_segment_fixed_size 0
		.amdhsa_kernarg_size 384
		.amdhsa_user_sgpr_count 2
		.amdhsa_user_sgpr_dispatch_ptr 0
		.amdhsa_user_sgpr_queue_ptr 0
		.amdhsa_user_sgpr_kernarg_segment_ptr 1
		.amdhsa_user_sgpr_dispatch_id 0
		.amdhsa_user_sgpr_kernarg_preload_length 0
		.amdhsa_user_sgpr_kernarg_preload_offset 0
		.amdhsa_user_sgpr_private_segment_size 0
		.amdhsa_uses_dynamic_stack 0
		.amdhsa_enable_private_segment 0
		.amdhsa_system_sgpr_workgroup_id_x 1
		.amdhsa_system_sgpr_workgroup_id_y 0
		.amdhsa_system_sgpr_workgroup_id_z 0
		.amdhsa_system_sgpr_workgroup_info 0
		.amdhsa_system_vgpr_workitem_id 2
		.amdhsa_next_free_vgpr 256
		.amdhsa_next_free_sgpr 100
		.amdhsa_accum_offset 256
		.amdhsa_reserve_vcc 1
		.amdhsa_float_round_mode_32 0
		.amdhsa_float_round_mode_16_64 0
		.amdhsa_float_denorm_mode_32 3
		.amdhsa_float_denorm_mode_16_64 3
		.amdhsa_dx10_clamp 1
		.amdhsa_ieee_mode 1
		.amdhsa_fp16_overflow 0
		.amdhsa_tg_split 0
		.amdhsa_exception_fp_ieee_invalid_op 0
		.amdhsa_exception_fp_denorm_src 0
		.amdhsa_exception_fp_ieee_div_zero 0
		.amdhsa_exception_fp_ieee_overflow 0
		.amdhsa_exception_fp_ieee_underflow 0
		.amdhsa_exception_fp_ieee_inexact 0
		.amdhsa_exception_int_div_zero 0
	.end_amdhsa_kernel

; __global__ void __launch_bounds__(512, 2) fwd_megakernel(Params p) {
amdhsa.kernels:
  - .agpr_count:     0
    .args:
      - .offset:         0
        .size:           128
        .value_kind:     by_value
      - .offset:         128
        .size:           4
        .value_kind:     hidden_block_count_x
      - .offset:         132
        .size:           4
        .value_kind:     hidden_block_count_y
      - .offset:         136
        .size:           4
        .value_kind:     hidden_block_count_z
      - .offset:         140
        .size:           2
        .value_kind:     hidden_group_size_x
      - .offset:         142
        .size:           2
        .value_kind:     hidden_group_size_y
      - .offset:         144
        .size:           2
        .value_kind:     hidden_group_size_z
      - .offset:         146
        .size:           2
        .value_kind:     hidden_remainder_x
      - .offset:         148
        .size:           2
        .value_kind:     hidden_remainder_y
      - .offset:         150
        .size:           2
        .value_kind:     hidden_remainder_z
      - .offset:         168
        .size:           8
        .value_kind:     hidden_global_offset_x
      - .offset:         176
        .size:           8
        .value_kind:     hidden_global_offset_y
      - .offset:         184
        .size:           8
        .value_kind:     hidden_global_offset_z
      - .offset:         192
        .size:           2
        .value_kind:     hidden_grid_dims
      - .offset:         216
        .size:           8
        .value_kind:     hidden_multigrid_sync_arg
      - .offset:         248
        .size:           4
        .value_kind:     hidden_dynamic_lds_size
    .group_segment_fixed_size: 0
    .kernarg_segment_align: 8
    .kernarg_segment_size: 384
    .language:       OpenCL C
    .language_version:
      - 2
      - 0
    .max_flat_workgroup_size: 512
    .name:           _Z14fwd_megakernel6Params
    .private_segment_fixed_size: 0
    .sgpr_count:     106
    .sgpr_spill_count: 61
    .symbol:         _Z14fwd_megakernel6Params.kd
    .uniform_work_group_size: 1
    .uses_dynamic_stack: false
    .vgpr_count:     256
    .vgpr_spill_count: 0
    .wavefront_size: 64
